# barrier release: the XCD leader bumps all 16 replicated release counters with ONE 16-lane atomic instruction instead of 16 sequential single-lane atomics
# speedup vs baseline: 1.0023x; 1.0023x over previous
; __device__ __forceinline__ unsigned xb_ld(unsigned* p)              { return __hip_atomic_load(p, __ATOMIC_RELAXED, __HIP_MEMORY_SCOPE_AGENT); }
; __device__ __forceinline__ unsigned xb_add(unsigned* p, unsigned v) { return __hip_atomic_fetch_add(p, v, __ATOMIC_RELAXED, __HIP_MEMORY_SCOPE_AGENT); }
; #define XB_SPIN(cond, bar) do { unsigned _sp = 0; while (cond) { __builtin_amdgcn_s_sleep(1); \
;     if ((++_sp & 255u) == 0u) { if (xb_ld(&(bar)[XB_TMO])) break; if (_sp > XB_SPIN_CAP) { atomicAdd(&(bar)[XB_TMO], 1u); break; } } } } while (0)
; __device__ __forceinline__ void xcd_barrier(const XcdBarrier& b) {
;     asm volatile("s_waitcnt vmcnt(0)" ::: "memory");
;     __syncthreads();
;     if (threadIdx.x == 0) {
;         unsigned* bar = b.bar;
;         __builtin_amdgcn_s_waitcnt(0);
;         unsigned nloc = b.st[0], nx = b.st[1];
;         if (nloc == 0u) { xcd_barrier_complete(bar, b.x, nloc, nx); b.st[0] = nloc; b.st[1] = nx; }
;         const unsigned old = xb_add(&bar[XB_XSUB(b.x)], 1u);
;         const unsigned gen = old / nloc;
;         if (old + 1u == (gen + 1u) * nloc) {
;             __builtin_amdgcn_fence(__ATOMIC_RELEASE, "agent");
;             asm volatile("s_waitcnt vmcnt(0)" ::: "memory");
;             const unsigned og = xb_add(&bar[XB_TOP], 1u);
;             const unsigned tg = og / nx;
;             if (og + 1u == (tg + 1u) * nx) xb_add(&bar[XB_TOPGEN], 1u);
;             else XB_SPIN(xb_ld(&bar[XB_TOPGEN]) == tg, bar);
;             __builtin_amdgcn_fence(__ATOMIC_ACQUIRE, "agent");
;             xb_add(&bar[XB_XGEN(b.x)], 1u);
;             asm volatile("s_waitcnt vmcnt(0)" ::: "memory");
;         } else {
;             XB_SPIN(xb_ld(&bar[XB_XGEN(b.x)]) == gen, bar);
;             __builtin_amdgcn_fence(__ATOMIC_ACQUIRE, "agent");
;             asm volatile("s_waitcnt vmcnt(0)" ::: "memory");
;         }
;     }
;     __syncthreads();
; }
.LBB0_161:
	s_getreg_b32 s4, hwreg(HW_REG_XCC_ID, 0, 4)
	s_waitcnt vmcnt(0)
	s_waitcnt vmcnt(0)
	s_barrier
	s_and_saveexec_b64 s[0:1], s[68:69]
	v_readlane_b32 s28, v254, 58
	s_xor_b64 s[0:1], exec, s[0:1]
	v_readlane_b32 s29, v254, 59
	s_cbranch_execz .LBB0_214
	v_readlane_b32 s2, v254, 42
	s_waitcnt vmcnt(0) expcnt(0) lgkmcnt(0)
	buffer_inv sc1
	s_and_b32 s10, s4, 15
	s_lshl_b32 s5, s10, 8
	v_mov_b32_e32 v0, s2
	ds_read_b32 v2, v0
	v_readlane_b32 s2, v254, 43
	s_add_u32 s12, s46, s5
	s_addc_u32 s13, s47, 0
	v_mov_b32_e32 v3, 1
	v_mov_b32_e32 v0, s2
	ds_read_b32 v6, v0
	v_mov_b32_e32 v5, 0x1400
	s_waitcnt lgkmcnt(0)
	global_atomic_add v3, v5, v3, s[12:13] sc0
	v_cvt_f32_u32_e32 v4, v2
	s_waitcnt vmcnt(0)
	v_mov_b32_e32 v5, v3
	v_sub_u32_e32 v3, 0, v2
	v_rcp_iflag_f32_e32 v4, v4
	s_nop 0
	v_mul_f32_e32 v4, 0x4f7ffffe, v4
	v_cvt_u32_f32_e32 v4, v4
	v_mul_lo_u32 v1, v3, v4
	v_mul_hi_u32 v1, v4, v1
	v_add_u32_e32 v1, v4, v1
	v_mul_hi_u32 v1, v5, v1
	v_mul_lo_u32 v3, v1, v2
	v_sub_u32_e32 v3, v5, v3
	v_add_u32_e32 v4, 1, v1
	v_cmp_ge_u32_e32 vcc, v3, v2
	s_nop 1
	v_cndmask_b32_e32 v1, v1, v4, vcc
	v_sub_u32_e32 v4, v3, v2
	v_cndmask_b32_e32 v3, v3, v4, vcc
	v_add_u32_e32 v4, 1, v1
	v_cmp_ge_u32_e32 vcc, v3, v2
	v_add_u32_e32 v3, 1, v5
	s_nop 0
	v_cndmask_b32_e32 v1, v1, v4, vcc
	v_mul_lo_u32 v4, v2, v1
	v_add_u32_e32 v2, v4, v2
	v_mul_lo_u32 v7, v1, v6
	v_cmp_ne_u32_e32 vcc, v3, v2
	s_mov_b32 s8, 0
	s_cbranch_vccnz .Lnb_loop_1
	buffer_wbl2 sc1
	s_waitcnt vmcnt(0)
	s_mov_b64 exec, 0xffff
	v_mbcnt_lo_u32_b32 v9, -1, 0
	v_mov_b32_e32 v8, 1
	v_lshlrev_b32_e32 v9, 8, v9
	v_add_u32_e32 v9, 0x2404, v9
	global_atomic_add v9, v8, s[46:47]
	s_mov_b64 exec, 1

; __device__ __forceinline__ unsigned xb_ld(unsigned* p)              { return __hip_atomic_load(p, __ATOMIC_RELAXED, __HIP_MEMORY_SCOPE_AGENT); }
; __device__ __forceinline__ unsigned xb_add(unsigned* p, unsigned v) { return __hip_atomic_fetch_add(p, v, __ATOMIC_RELAXED, __HIP_MEMORY_SCOPE_AGENT); }
; #define XB_SPIN(cond, bar) do { unsigned _sp = 0; while (cond) { __builtin_amdgcn_s_sleep(1); \
;     if ((++_sp & 255u) == 0u) { if (xb_ld(&(bar)[XB_TMO])) break; if (_sp > XB_SPIN_CAP) { atomicAdd(&(bar)[XB_TMO], 1u); break; } } } } while (0)
; __device__ __forceinline__ void xcd_barrier(const XcdBarrier& b) {
;     asm volatile("s_waitcnt vmcnt(0)" ::: "memory");
;     __syncthreads();
;     if (threadIdx.x == 0) {
;         unsigned* bar = b.bar;
;         __builtin_amdgcn_s_waitcnt(0);
;         unsigned nloc = b.st[0], nx = b.st[1];
;         if (nloc == 0u) { xcd_barrier_complete(bar, b.x, nloc, nx); b.st[0] = nloc; b.st[1] = nx; }
;         const unsigned old = xb_add(&bar[XB_XSUB(b.x)], 1u);
;         const unsigned gen = old / nloc;
;         if (old + 1u == (gen + 1u) * nloc) {
;             __builtin_amdgcn_fence(__ATOMIC_RELEASE, "agent");
;             asm volatile("s_waitcnt vmcnt(0)" ::: "memory");
;             const unsigned og = xb_add(&bar[XB_TOP], 1u);
;             const unsigned tg = og / nx;
;             if (og + 1u == (tg + 1u) * nx) xb_add(&bar[XB_TOPGEN], 1u);
;             else XB_SPIN(xb_ld(&bar[XB_TOPGEN]) == tg, bar);
;             __builtin_amdgcn_fence(__ATOMIC_ACQUIRE, "agent");
;             xb_add(&bar[XB_XGEN(b.x)], 1u);
;             asm volatile("s_waitcnt vmcnt(0)" ::: "memory");
;         } else {
;             XB_SPIN(xb_ld(&bar[XB_XGEN(b.x)]) == gen, bar);
;             __builtin_amdgcn_fence(__ATOMIC_ACQUIRE, "agent");
;             asm volatile("s_waitcnt vmcnt(0)" ::: "memory");
;         }
;     }
;     __syncthreads();
; }
.LBB0_218:
	s_getreg_b32 s4, hwreg(HW_REG_XCC_ID, 0, 4)
	s_waitcnt vmcnt(0)
	s_mov_b64 s[48:49], 0x3000
	s_mov_b64 s[62:63], 0x3800
	s_mov_b64 s[96:97], 0x1c00
	s_mov_b64 s[50:51], 0x2c00
	s_mov_b64 s[58:59], 0x2800
	s_mov_b64 s[56:57], 0x2400
	s_mov_b64 s[54:55], 0x2000
	s_waitcnt lgkmcnt(0)
	s_barrier
	s_and_saveexec_b64 s[0:1], s[68:69]
	s_cbranch_execz .LBB0_270
	v_readlane_b32 s2, v254, 42
	s_waitcnt vmcnt(0) expcnt(0) lgkmcnt(0)
	buffer_inv sc1
	s_and_b32 s10, s4, 15
	s_lshl_b32 s5, s10, 8
	v_mov_b32_e32 v0, s2
	ds_read_b32 v2, v0
	v_readlane_b32 s2, v254, 43
	s_add_u32 s12, s46, s5
	s_addc_u32 s13, s47, 0
	v_mov_b32_e32 v3, 1
	v_mov_b32_e32 v0, s2
	ds_read_b32 v6, v0
	v_mov_b32_e32 v5, 0x1400
	s_waitcnt lgkmcnt(0)
	global_atomic_add v3, v5, v3, s[12:13] sc0
	v_cvt_f32_u32_e32 v4, v2
	s_waitcnt vmcnt(0)
	v_mov_b32_e32 v5, v3
	v_sub_u32_e32 v3, 0, v2
	v_rcp_iflag_f32_e32 v4, v4
	s_nop 0
	v_mul_f32_e32 v4, 0x4f7ffffe, v4
	v_cvt_u32_f32_e32 v4, v4
	v_mul_lo_u32 v1, v3, v4
	v_mul_hi_u32 v1, v4, v1
	v_add_u32_e32 v1, v4, v1
	v_mul_hi_u32 v1, v5, v1
	v_mul_lo_u32 v3, v1, v2
	v_sub_u32_e32 v3, v5, v3
	v_add_u32_e32 v4, 1, v1
	v_cmp_ge_u32_e32 vcc, v3, v2
	s_nop 1
	v_cndmask_b32_e32 v1, v1, v4, vcc
	v_sub_u32_e32 v4, v3, v2
	v_cndmask_b32_e32 v3, v3, v4, vcc
	v_add_u32_e32 v4, 1, v1
	v_cmp_ge_u32_e32 vcc, v3, v2
	v_add_u32_e32 v3, 1, v5
	s_nop 0
	v_cndmask_b32_e32 v1, v1, v4, vcc
	v_mul_lo_u32 v4, v2, v1
	v_add_u32_e32 v2, v4, v2
	v_mul_lo_u32 v7, v1, v6
	v_cmp_ne_u32_e32 vcc, v3, v2
	s_mov_b32 s8, 0
	s_cbranch_vccnz .Lnb_loop_2
	buffer_wbl2 sc1
	s_waitcnt vmcnt(0)
	s_mov_b64 exec, 0xffff
	v_mbcnt_lo_u32_b32 v9, -1, 0
	v_mov_b32_e32 v8, 1
	v_lshlrev_b32_e32 v9, 8, v9
	v_add_u32_e32 v9, 0x2404, v9
	global_atomic_add v9, v8, s[46:47]
	s_mov_b64 exec, 1

; __device__ __forceinline__ unsigned xb_ld(unsigned* p)              { return __hip_atomic_load(p, __ATOMIC_RELAXED, __HIP_MEMORY_SCOPE_AGENT); }
; __device__ __forceinline__ unsigned xb_add(unsigned* p, unsigned v) { return __hip_atomic_fetch_add(p, v, __ATOMIC_RELAXED, __HIP_MEMORY_SCOPE_AGENT); }
; #define XB_SPIN(cond, bar) do { unsigned _sp = 0; while (cond) { __builtin_amdgcn_s_sleep(1); \
;     if ((++_sp & 255u) == 0u) { if (xb_ld(&(bar)[XB_TMO])) break; if (_sp > XB_SPIN_CAP) { atomicAdd(&(bar)[XB_TMO], 1u); break; } } } } while (0)
; __device__ __forceinline__ void xcd_barrier(const XcdBarrier& b) {
;     asm volatile("s_waitcnt vmcnt(0)" ::: "memory");
;     __syncthreads();
;     if (threadIdx.x == 0) {
;         unsigned* bar = b.bar;
;         __builtin_amdgcn_s_waitcnt(0);
;         unsigned nloc = b.st[0], nx = b.st[1];
;         if (nloc == 0u) { xcd_barrier_complete(bar, b.x, nloc, nx); b.st[0] = nloc; b.st[1] = nx; }
;         const unsigned old = xb_add(&bar[XB_XSUB(b.x)], 1u);
;         const unsigned gen = old / nloc;
;         if (old + 1u == (gen + 1u) * nloc) {
;             __builtin_amdgcn_fence(__ATOMIC_RELEASE, "agent");
;             asm volatile("s_waitcnt vmcnt(0)" ::: "memory");
;             const unsigned og = xb_add(&bar[XB_TOP], 1u);
;             const unsigned tg = og / nx;
;             if (og + 1u == (tg + 1u) * nx) xb_add(&bar[XB_TOPGEN], 1u);
;             else XB_SPIN(xb_ld(&bar[XB_TOPGEN]) == tg, bar);
;             __builtin_amdgcn_fence(__ATOMIC_ACQUIRE, "agent");
;             xb_add(&bar[XB_XGEN(b.x)], 1u);
;             asm volatile("s_waitcnt vmcnt(0)" ::: "memory");
;         } else {
;             XB_SPIN(xb_ld(&bar[XB_XGEN(b.x)]) == gen, bar);
;             __builtin_amdgcn_fence(__ATOMIC_ACQUIRE, "agent");
;             asm volatile("s_waitcnt vmcnt(0)" ::: "memory");
;         }
;     }
;     __syncthreads();
; }
.LBB0_275:
	s_or_b64 exec, exec, s[0:1]
	s_getreg_b32 s4, hwreg(HW_REG_XCC_ID, 0, 4)
	s_waitcnt vmcnt(0)
	s_barrier
	s_and_saveexec_b64 s[0:1], s[68:69]
	s_cbranch_execz .LBB0_327
	v_readlane_b32 s2, v254, 42
	s_waitcnt vmcnt(0) expcnt(0) lgkmcnt(0)
	buffer_inv sc1
	s_and_b32 s10, s4, 15
	s_lshl_b32 s5, s10, 8
	v_mov_b32_e32 v0, s2
	ds_read_b32 v2, v0
	v_readlane_b32 s2, v254, 43
	s_add_u32 s12, s46, s5
	s_addc_u32 s13, s47, 0
	v_mov_b32_e32 v3, 1
	v_mov_b32_e32 v0, s2
	ds_read_b32 v6, v0
	v_mov_b32_e32 v5, 0x1400
	s_waitcnt lgkmcnt(0)
	global_atomic_add v3, v5, v3, s[12:13] sc0
	v_cvt_f32_u32_e32 v4, v2
	s_waitcnt vmcnt(0)
	v_mov_b32_e32 v5, v3
	v_sub_u32_e32 v3, 0, v2
	v_rcp_iflag_f32_e32 v4, v4
	s_nop 0
	v_mul_f32_e32 v4, 0x4f7ffffe, v4
	v_cvt_u32_f32_e32 v4, v4
	v_mul_lo_u32 v1, v3, v4
	v_mul_hi_u32 v1, v4, v1
	v_add_u32_e32 v1, v4, v1
	v_mul_hi_u32 v1, v5, v1
	v_mul_lo_u32 v3, v1, v2
	v_sub_u32_e32 v3, v5, v3
	v_add_u32_e32 v4, 1, v1
	v_cmp_ge_u32_e32 vcc, v3, v2
	s_nop 1
	v_cndmask_b32_e32 v1, v1, v4, vcc
	v_sub_u32_e32 v4, v3, v2
	v_cndmask_b32_e32 v3, v3, v4, vcc
	v_add_u32_e32 v4, 1, v1
	v_cmp_ge_u32_e32 vcc, v3, v2
	v_add_u32_e32 v3, 1, v5
	s_nop 0
	v_cndmask_b32_e32 v1, v1, v4, vcc
	v_mul_lo_u32 v4, v2, v1
	v_add_u32_e32 v2, v4, v2
	v_mul_lo_u32 v7, v1, v6
	v_cmp_ne_u32_e32 vcc, v3, v2
	s_mov_b32 s8, 0
	s_cbranch_vccnz .Lnb_loop_3
	buffer_wbl2 sc1
	s_waitcnt vmcnt(0)
	s_mov_b64 exec, 0xffff
	v_mbcnt_lo_u32_b32 v9, -1, 0
	v_mov_b32_e32 v8, 1
	v_lshlrev_b32_e32 v9, 8, v9
	v_add_u32_e32 v9, 0x2404, v9
	global_atomic_add v9, v8, s[46:47]
	s_mov_b64 exec, 1

; __device__ __forceinline__ unsigned xb_ld(unsigned* p)              { return __hip_atomic_load(p, __ATOMIC_RELAXED, __HIP_MEMORY_SCOPE_AGENT); }
; __device__ __forceinline__ unsigned xb_add(unsigned* p, unsigned v) { return __hip_atomic_fetch_add(p, v, __ATOMIC_RELAXED, __HIP_MEMORY_SCOPE_AGENT); }
; #define XB_SPIN(cond, bar) do { unsigned _sp = 0; while (cond) { __builtin_amdgcn_s_sleep(1); \
;     if ((++_sp & 255u) == 0u) { if (xb_ld(&(bar)[XB_TMO])) break; if (_sp > XB_SPIN_CAP) { atomicAdd(&(bar)[XB_TMO], 1u); break; } } } } while (0)
; __device__ __forceinline__ void xcd_barrier(const XcdBarrier& b) {
;     asm volatile("s_waitcnt vmcnt(0)" ::: "memory");
;     __syncthreads();
;     if (threadIdx.x == 0) {
;         unsigned* bar = b.bar;
;         __builtin_amdgcn_s_waitcnt(0);
;         unsigned nloc = b.st[0], nx = b.st[1];
;         if (nloc == 0u) { xcd_barrier_complete(bar, b.x, nloc, nx); b.st[0] = nloc; b.st[1] = nx; }
;         const unsigned old = xb_add(&bar[XB_XSUB(b.x)], 1u);
;         const unsigned gen = old / nloc;
;         if (old + 1u == (gen + 1u) * nloc) {
;             __builtin_amdgcn_fence(__ATOMIC_RELEASE, "agent");
;             asm volatile("s_waitcnt vmcnt(0)" ::: "memory");
;             const unsigned og = xb_add(&bar[XB_TOP], 1u);
;             const unsigned tg = og / nx;
;             if (og + 1u == (tg + 1u) * nx) xb_add(&bar[XB_TOPGEN], 1u);
;             else XB_SPIN(xb_ld(&bar[XB_TOPGEN]) == tg, bar);
;             __builtin_amdgcn_fence(__ATOMIC_ACQUIRE, "agent");
;             xb_add(&bar[XB_XGEN(b.x)], 1u);
;             asm volatile("s_waitcnt vmcnt(0)" ::: "memory");
;         } else {
;             XB_SPIN(xb_ld(&bar[XB_XGEN(b.x)]) == gen, bar);
;             __builtin_amdgcn_fence(__ATOMIC_ACQUIRE, "agent");
;             asm volatile("s_waitcnt vmcnt(0)" ::: "memory");
;         }
;     }
;     __syncthreads();
; }
.LBB0_339:
	s_getreg_b32 s4, hwreg(HW_REG_XCC_ID, 0, 4)
	s_waitcnt vmcnt(0)
	s_barrier
	s_and_saveexec_b64 s[0:1], s[68:69]
	v_readlane_b32 s24, v254, 63
	s_xor_b64 s[0:1], exec, s[0:1]
	v_readlane_b32 s25, v255, 0
	s_cbranch_execz .LBB0_392
	v_readlane_b32 s2, v254, 42
	s_waitcnt vmcnt(0) expcnt(0) lgkmcnt(0)
	buffer_inv sc1
	s_and_b32 s10, s4, 15
	s_lshl_b32 s5, s10, 8
	v_mov_b32_e32 v0, s2
	ds_read_b32 v2, v0
	v_readlane_b32 s2, v254, 43
	s_add_u32 s12, s46, s5
	s_addc_u32 s13, s47, 0
	v_mov_b32_e32 v3, 1
	v_mov_b32_e32 v0, s2
	ds_read_b32 v6, v0
	v_mov_b32_e32 v5, 0x1400
	s_waitcnt lgkmcnt(0)
	global_atomic_add v3, v5, v3, s[12:13] sc0
	v_cvt_f32_u32_e32 v4, v2
	s_waitcnt vmcnt(0)
	v_mov_b32_e32 v5, v3
	v_sub_u32_e32 v3, 0, v2
	v_rcp_iflag_f32_e32 v4, v4
	s_nop 0
	v_mul_f32_e32 v4, 0x4f7ffffe, v4
	v_cvt_u32_f32_e32 v4, v4
	v_mul_lo_u32 v1, v3, v4
	v_mul_hi_u32 v1, v4, v1
	v_add_u32_e32 v1, v4, v1
	v_mul_hi_u32 v1, v5, v1
	v_mul_lo_u32 v3, v1, v2
	v_sub_u32_e32 v3, v5, v3
	v_add_u32_e32 v4, 1, v1
	v_cmp_ge_u32_e32 vcc, v3, v2
	s_nop 1
	v_cndmask_b32_e32 v1, v1, v4, vcc
	v_sub_u32_e32 v4, v3, v2
	v_cndmask_b32_e32 v3, v3, v4, vcc
	v_add_u32_e32 v4, 1, v1
	v_cmp_ge_u32_e32 vcc, v3, v2
	v_add_u32_e32 v3, 1, v5
	s_nop 0
	v_cndmask_b32_e32 v1, v1, v4, vcc
	v_mul_lo_u32 v4, v2, v1
	v_add_u32_e32 v2, v4, v2
	v_mul_lo_u32 v7, v1, v6
	v_cmp_ne_u32_e32 vcc, v3, v2
	s_mov_b32 s8, 0
	s_cbranch_vccnz .Lnb_loop_4
	buffer_wbl2 sc1
	s_waitcnt vmcnt(0)
	s_mov_b64 exec, 0xffff
	v_mbcnt_lo_u32_b32 v9, -1, 0
	v_mov_b32_e32 v8, 1
	v_lshlrev_b32_e32 v9, 8, v9
	v_add_u32_e32 v9, 0x2404, v9
	global_atomic_add v9, v8, s[46:47]
	s_mov_b64 exec, 1

; __device__ __forceinline__ unsigned xb_ld(unsigned* p)              { return __hip_atomic_load(p, __ATOMIC_RELAXED, __HIP_MEMORY_SCOPE_AGENT); }
; __device__ __forceinline__ unsigned xb_add(unsigned* p, unsigned v) { return __hip_atomic_fetch_add(p, v, __ATOMIC_RELAXED, __HIP_MEMORY_SCOPE_AGENT); }
; #define XB_SPIN(cond, bar) do { unsigned _sp = 0; while (cond) { __builtin_amdgcn_s_sleep(1); \
;     if ((++_sp & 255u) == 0u) { if (xb_ld(&(bar)[XB_TMO])) break; if (_sp > XB_SPIN_CAP) { atomicAdd(&(bar)[XB_TMO], 1u); break; } } } } while (0)
; __device__ __forceinline__ void xcd_barrier(const XcdBarrier& b) {
;     asm volatile("s_waitcnt vmcnt(0)" ::: "memory");
;     __syncthreads();
;     if (threadIdx.x == 0) {
;         unsigned* bar = b.bar;
;         __builtin_amdgcn_s_waitcnt(0);
;         unsigned nloc = b.st[0], nx = b.st[1];
;         if (nloc == 0u) { xcd_barrier_complete(bar, b.x, nloc, nx); b.st[0] = nloc; b.st[1] = nx; }
;         const unsigned old = xb_add(&bar[XB_XSUB(b.x)], 1u);
;         const unsigned gen = old / nloc;
;         if (old + 1u == (gen + 1u) * nloc) {
;             __builtin_amdgcn_fence(__ATOMIC_RELEASE, "agent");
;             asm volatile("s_waitcnt vmcnt(0)" ::: "memory");
;             const unsigned og = xb_add(&bar[XB_TOP], 1u);
;             const unsigned tg = og / nx;
;             if (og + 1u == (tg + 1u) * nx) xb_add(&bar[XB_TOPGEN], 1u);
;             else XB_SPIN(xb_ld(&bar[XB_TOPGEN]) == tg, bar);
;             __builtin_amdgcn_fence(__ATOMIC_ACQUIRE, "agent");
;             xb_add(&bar[XB_XGEN(b.x)], 1u);
;             asm volatile("s_waitcnt vmcnt(0)" ::: "memory");
;         } else {
;             XB_SPIN(xb_ld(&bar[XB_XGEN(b.x)]) == gen, bar);
;             __builtin_amdgcn_fence(__ATOMIC_ACQUIRE, "agent");
;             asm volatile("s_waitcnt vmcnt(0)" ::: "memory");
;         }
;     }
;     __syncthreads();
; }
.LBB0_469:
	s_getreg_b32 s4, hwreg(HW_REG_XCC_ID, 0, 4)
	s_waitcnt vmcnt(0)
	s_waitcnt lgkmcnt(0)
	s_barrier
	s_and_saveexec_b64 s[0:1], s[68:69]
	s_cbranch_execz .LBB0_521
	v_readlane_b32 s2, v254, 42
	s_waitcnt vmcnt(0) expcnt(0) lgkmcnt(0)
	buffer_inv sc1
	s_and_b32 s10, s4, 15
	s_lshl_b32 s5, s10, 8
	v_mov_b32_e32 v0, s2
	ds_read_b32 v2, v0
	v_readlane_b32 s2, v254, 43
	s_add_u32 s12, s46, s5
	s_addc_u32 s13, s47, 0
	v_mov_b32_e32 v3, 1
	v_mov_b32_e32 v0, s2
	ds_read_b32 v6, v0
	v_mov_b32_e32 v5, 0x1400
	s_waitcnt lgkmcnt(0)
	global_atomic_add v3, v5, v3, s[12:13] sc0
	v_cvt_f32_u32_e32 v4, v2
	s_waitcnt vmcnt(0)
	v_mov_b32_e32 v5, v3
	v_sub_u32_e32 v3, 0, v2
	v_rcp_iflag_f32_e32 v4, v4
	s_nop 0
	v_mul_f32_e32 v4, 0x4f7ffffe, v4
	v_cvt_u32_f32_e32 v4, v4
	v_mul_lo_u32 v1, v3, v4
	v_mul_hi_u32 v1, v4, v1
	v_add_u32_e32 v1, v4, v1
	v_mul_hi_u32 v1, v5, v1
	v_mul_lo_u32 v3, v1, v2
	v_sub_u32_e32 v3, v5, v3
	v_add_u32_e32 v4, 1, v1
	v_cmp_ge_u32_e32 vcc, v3, v2
	s_nop 1
	v_cndmask_b32_e32 v1, v1, v4, vcc
	v_sub_u32_e32 v4, v3, v2
	v_cndmask_b32_e32 v3, v3, v4, vcc
	v_add_u32_e32 v4, 1, v1
	v_cmp_ge_u32_e32 vcc, v3, v2
	v_add_u32_e32 v3, 1, v5
	s_nop 0
	v_cndmask_b32_e32 v1, v1, v4, vcc
	v_mul_lo_u32 v4, v2, v1
	v_add_u32_e32 v2, v4, v2
	v_mul_lo_u32 v7, v1, v6
	v_cmp_ne_u32_e32 vcc, v3, v2
	s_mov_b32 s8, 0
	s_cbranch_vccnz .Lnb_loop_5
	buffer_wbl2 sc1
	s_waitcnt vmcnt(0)
	s_mov_b64 exec, 0xffff
	v_mbcnt_lo_u32_b32 v9, -1, 0
	v_mov_b32_e32 v8, 1
	v_lshlrev_b32_e32 v9, 8, v9
	v_add_u32_e32 v9, 0x2404, v9
	global_atomic_add v9, v8, s[46:47]
	s_mov_b64 exec, 1

; __device__ __forceinline__ unsigned xb_ld(unsigned* p)              { return __hip_atomic_load(p, __ATOMIC_RELAXED, __HIP_MEMORY_SCOPE_AGENT); }
; __device__ __forceinline__ unsigned xb_add(unsigned* p, unsigned v) { return __hip_atomic_fetch_add(p, v, __ATOMIC_RELAXED, __HIP_MEMORY_SCOPE_AGENT); }
; #define XB_SPIN(cond, bar) do { unsigned _sp = 0; while (cond) { __builtin_amdgcn_s_sleep(1); \
;     if ((++_sp & 255u) == 0u) { if (xb_ld(&(bar)[XB_TMO])) break; if (_sp > XB_SPIN_CAP) { atomicAdd(&(bar)[XB_TMO], 1u); break; } } } } while (0)
; __device__ __forceinline__ void xcd_barrier(const XcdBarrier& b) {
;     asm volatile("s_waitcnt vmcnt(0)" ::: "memory");
;     __syncthreads();
;     if (threadIdx.x == 0) {
;         unsigned* bar = b.bar;
;         __builtin_amdgcn_s_waitcnt(0);
;         unsigned nloc = b.st[0], nx = b.st[1];
;         if (nloc == 0u) { xcd_barrier_complete(bar, b.x, nloc, nx); b.st[0] = nloc; b.st[1] = nx; }
;         const unsigned old = xb_add(&bar[XB_XSUB(b.x)], 1u);
;         const unsigned gen = old / nloc;
;         if (old + 1u == (gen + 1u) * nloc) {
;             __builtin_amdgcn_fence(__ATOMIC_RELEASE, "agent");
;             asm volatile("s_waitcnt vmcnt(0)" ::: "memory");
;             const unsigned og = xb_add(&bar[XB_TOP], 1u);
;             const unsigned tg = og / nx;
;             if (og + 1u == (tg + 1u) * nx) xb_add(&bar[XB_TOPGEN], 1u);
;             else XB_SPIN(xb_ld(&bar[XB_TOPGEN]) == tg, bar);
;             __builtin_amdgcn_fence(__ATOMIC_ACQUIRE, "agent");
;             xb_add(&bar[XB_XGEN(b.x)], 1u);
;             asm volatile("s_waitcnt vmcnt(0)" ::: "memory");
;         } else {
;             XB_SPIN(xb_ld(&bar[XB_XGEN(b.x)]) == gen, bar);
;             __builtin_amdgcn_fence(__ATOMIC_ACQUIRE, "agent");
;             asm volatile("s_waitcnt vmcnt(0)" ::: "memory");
;         }
;     }
;     __syncthreads();
; }
.LBB0_606:
	s_getreg_b32 s4, hwreg(HW_REG_XCC_ID, 0, 4)
	s_waitcnt vmcnt(0)
	s_barrier
	s_and_saveexec_b64 s[0:1], s[68:69]
	s_xor_b64 s[0:1], exec, s[0:1]
	s_cbranch_execz .LBB0_659
	v_readlane_b32 s2, v254, 42
	s_waitcnt vmcnt(0) expcnt(0) lgkmcnt(0)
	buffer_inv sc1
	s_and_b32 s10, s4, 15
	s_lshl_b32 s5, s10, 8
	v_mov_b32_e32 v0, s2
	ds_read_b32 v2, v0
	v_readlane_b32 s2, v254, 43
	s_add_u32 s12, s46, s5
	s_addc_u32 s13, s47, 0
	v_mov_b32_e32 v3, 1
	v_mov_b32_e32 v0, s2
	ds_read_b32 v6, v0
	v_mov_b32_e32 v5, 0x1400
	s_waitcnt lgkmcnt(0)
	global_atomic_add v3, v5, v3, s[12:13] sc0
	v_cvt_f32_u32_e32 v4, v2
	s_waitcnt vmcnt(0)
	v_mov_b32_e32 v5, v3
	v_sub_u32_e32 v3, 0, v2
	v_rcp_iflag_f32_e32 v4, v4
	s_nop 0
	v_mul_f32_e32 v4, 0x4f7ffffe, v4
	v_cvt_u32_f32_e32 v4, v4
	v_mul_lo_u32 v1, v3, v4
	v_mul_hi_u32 v1, v4, v1
	v_add_u32_e32 v1, v4, v1
	v_mul_hi_u32 v1, v5, v1
	v_mul_lo_u32 v3, v1, v2
	v_sub_u32_e32 v3, v5, v3
	v_add_u32_e32 v4, 1, v1
	v_cmp_ge_u32_e32 vcc, v3, v2
	s_nop 1
	v_cndmask_b32_e32 v1, v1, v4, vcc
	v_sub_u32_e32 v4, v3, v2
	v_cndmask_b32_e32 v3, v3, v4, vcc
	v_add_u32_e32 v4, 1, v1
	v_cmp_ge_u32_e32 vcc, v3, v2
	v_add_u32_e32 v3, 1, v5
	s_nop 0
	v_cndmask_b32_e32 v1, v1, v4, vcc
	v_mul_lo_u32 v4, v2, v1
	v_add_u32_e32 v2, v4, v2
	v_mul_lo_u32 v7, v1, v6
	v_cmp_ne_u32_e32 vcc, v3, v2
	s_mov_b32 s8, 0
	s_cbranch_vccnz .Lnb_loop_7
	buffer_wbl2 sc1
	s_waitcnt vmcnt(0)
	s_mov_b64 exec, 0xffff
	v_mbcnt_lo_u32_b32 v9, -1, 0
	v_mov_b32_e32 v8, 1
	v_lshlrev_b32_e32 v9, 8, v9
	v_add_u32_e32 v9, 0x2404, v9
	global_atomic_add v9, v8, s[46:47]
	s_mov_b64 exec, 1

; __device__ __forceinline__ unsigned xb_ld(unsigned* p)              { return __hip_atomic_load(p, __ATOMIC_RELAXED, __HIP_MEMORY_SCOPE_AGENT); }
; __device__ __forceinline__ unsigned xb_add(unsigned* p, unsigned v) { return __hip_atomic_fetch_add(p, v, __ATOMIC_RELAXED, __HIP_MEMORY_SCOPE_AGENT); }
; #define XB_SPIN(cond, bar) do { unsigned _sp = 0; while (cond) { __builtin_amdgcn_s_sleep(1); \
;     if ((++_sp & 255u) == 0u) { if (xb_ld(&(bar)[XB_TMO])) break; if (_sp > XB_SPIN_CAP) { atomicAdd(&(bar)[XB_TMO], 1u); break; } } } } while (0)
; __device__ __forceinline__ void xcd_barrier(const XcdBarrier& b) {
;     asm volatile("s_waitcnt vmcnt(0)" ::: "memory");
;     __syncthreads();
;     if (threadIdx.x == 0) {
;         unsigned* bar = b.bar;
;         __builtin_amdgcn_s_waitcnt(0);
;         unsigned nloc = b.st[0], nx = b.st[1];
;         if (nloc == 0u) { xcd_barrier_complete(bar, b.x, nloc, nx); b.st[0] = nloc; b.st[1] = nx; }
;         const unsigned old = xb_add(&bar[XB_XSUB(b.x)], 1u);
;         const unsigned gen = old / nloc;
;         if (old + 1u == (gen + 1u) * nloc) {
;             __builtin_amdgcn_fence(__ATOMIC_RELEASE, "agent");
;             asm volatile("s_waitcnt vmcnt(0)" ::: "memory");
;             const unsigned og = xb_add(&bar[XB_TOP], 1u);
;             const unsigned tg = og / nx;
;             if (og + 1u == (tg + 1u) * nx) xb_add(&bar[XB_TOPGEN], 1u);
;             else XB_SPIN(xb_ld(&bar[XB_TOPGEN]) == tg, bar);
;             __builtin_amdgcn_fence(__ATOMIC_ACQUIRE, "agent");
;             xb_add(&bar[XB_XGEN(b.x)], 1u);
;             asm volatile("s_waitcnt vmcnt(0)" ::: "memory");
;         } else {
;             XB_SPIN(xb_ld(&bar[XB_XGEN(b.x)]) == gen, bar);
;             __builtin_amdgcn_fence(__ATOMIC_ACQUIRE, "agent");
;             asm volatile("s_waitcnt vmcnt(0)" ::: "memory");
;         }
;     }
;     __syncthreads();
; }
.LBB0_829:
	s_getreg_b32 s4, hwreg(HW_REG_XCC_ID, 0, 4)
	s_waitcnt vmcnt(0)
	s_waitcnt vmcnt(0) lgkmcnt(0)
	s_barrier
	s_and_saveexec_b64 s[0:1], s[68:69]
	v_readlane_b32 s26, v254, 49
	v_readlane_b32 s80, v254, 51
	s_xor_b64 s[0:1], exec, s[0:1]
	v_readlane_b32 s27, v254, 50
	v_readlane_b32 s81, v254, 52
	s_cbranch_execz .LBB0_882
	v_readlane_b32 s2, v254, 42
	s_waitcnt vmcnt(0) expcnt(0) lgkmcnt(0)
	buffer_inv sc1
	s_and_b32 s10, s4, 15
	s_lshl_b32 s5, s10, 8
	v_mov_b32_e32 v0, s2
	ds_read_b32 v2, v0
	v_readlane_b32 s2, v254, 43
	s_add_u32 s12, s46, s5
	s_addc_u32 s13, s47, 0
	v_mov_b32_e32 v3, 1
	v_mov_b32_e32 v0, s2
	ds_read_b32 v6, v0
	v_mov_b32_e32 v5, 0x1400
	s_waitcnt lgkmcnt(0)
	global_atomic_add v3, v5, v3, s[12:13] sc0
	v_cvt_f32_u32_e32 v4, v2
	s_waitcnt vmcnt(0)
	v_mov_b32_e32 v5, v3
	v_sub_u32_e32 v3, 0, v2
	v_rcp_iflag_f32_e32 v4, v4
	s_nop 0
	v_mul_f32_e32 v4, 0x4f7ffffe, v4
	v_cvt_u32_f32_e32 v4, v4
	v_mul_lo_u32 v1, v3, v4
	v_mul_hi_u32 v1, v4, v1
	v_add_u32_e32 v1, v4, v1
	v_mul_hi_u32 v1, v5, v1
	v_mul_lo_u32 v3, v1, v2
	v_sub_u32_e32 v3, v5, v3
	v_add_u32_e32 v4, 1, v1
	v_cmp_ge_u32_e32 vcc, v3, v2
	s_nop 1
	v_cndmask_b32_e32 v1, v1, v4, vcc
	v_sub_u32_e32 v4, v3, v2
	v_cndmask_b32_e32 v3, v3, v4, vcc
	v_add_u32_e32 v4, 1, v1
	v_cmp_ge_u32_e32 vcc, v3, v2
	v_add_u32_e32 v3, 1, v5
	s_nop 0
	v_cndmask_b32_e32 v1, v1, v4, vcc
	v_mul_lo_u32 v4, v2, v1
	v_add_u32_e32 v2, v4, v2
	v_mul_lo_u32 v7, v1, v6
	v_cmp_ne_u32_e32 vcc, v3, v2
	s_mov_b32 s8, 0
	s_cbranch_vccnz .Lnb_loop_10
	buffer_wbl2 sc1
	s_waitcnt vmcnt(0)
	s_mov_b64 exec, 0xffff
	v_mbcnt_lo_u32_b32 v9, -1, 0
	v_mov_b32_e32 v8, 1
	v_lshlrev_b32_e32 v9, 8, v9
	v_add_u32_e32 v9, 0x2404, v9
	global_atomic_add v9, v8, s[46:47]
	s_mov_b64 exec, 1

; __device__ __forceinline__ unsigned xb_ld(unsigned* p)              { return __hip_atomic_load(p, __ATOMIC_RELAXED, __HIP_MEMORY_SCOPE_AGENT); }
; __device__ __forceinline__ unsigned xb_add(unsigned* p, unsigned v) { return __hip_atomic_fetch_add(p, v, __ATOMIC_RELAXED, __HIP_MEMORY_SCOPE_AGENT); }
; #define XB_SPIN(cond, bar) do { unsigned _sp = 0; while (cond) { __builtin_amdgcn_s_sleep(1); \
;     if ((++_sp & 255u) == 0u) { if (xb_ld(&(bar)[XB_TMO])) break; if (_sp > XB_SPIN_CAP) { atomicAdd(&(bar)[XB_TMO], 1u); break; } } } } while (0)
; #define GSYNC() do { XcdBarrier b_; b_.bar = (unsigned*)args.ws; b_.x = xb_xcc_id(); b_.st = (volatile LAS unsigned*)((LAS unsigned char*)lds + LDS_BYTES - 64) + 8; xcd_barrier(b_); if constexpr ((DUP) & 0x10000) xcd_barrier(b_); } while (0)
; __device__ __forceinline__ void xcd_barrier(const XcdBarrier& b) {
;     asm volatile("s_waitcnt vmcnt(0)" ::: "memory");
;     __syncthreads();
;     if (threadIdx.x == 0) {
;         unsigned* bar = b.bar;
;         __builtin_amdgcn_s_waitcnt(0);
;         unsigned nloc = b.st[0], nx = b.st[1];
;         if (nloc == 0u) { xcd_barrier_complete(bar, b.x, nloc, nx); b.st[0] = nloc; b.st[1] = nx; }
;         const unsigned old = xb_add(&bar[XB_XSUB(b.x)], 1u);
;         const unsigned gen = old / nloc;
;         if (old + 1u == (gen + 1u) * nloc) {
;             __builtin_amdgcn_fence(__ATOMIC_RELEASE, "agent");
;             asm volatile("s_waitcnt vmcnt(0)" ::: "memory");
;             const unsigned og = xb_add(&bar[XB_TOP], 1u);
;             const unsigned tg = og / nx;
;             if (og + 1u == (tg + 1u) * nx) xb_add(&bar[XB_TOPGEN], 1u);
;             else XB_SPIN(xb_ld(&bar[XB_TOPGEN]) == tg, bar);
;             __builtin_amdgcn_fence(__ATOMIC_ACQUIRE, "agent");
;             xb_add(&bar[XB_XGEN(b.x)], 1u);
;             asm volatile("s_waitcnt vmcnt(0)" ::: "memory");
;         } else {
;             XB_SPIN(xb_ld(&bar[XB_XGEN(b.x)]) == gen, bar);
;             __builtin_amdgcn_fence(__ATOMIC_ACQUIRE, "agent");
;             asm volatile("s_waitcnt vmcnt(0)" ::: "memory");
;         }
;     }
;     __syncthreads();
; }
; __global__ void __launch_bounds__(NTHR, 2) fwd_megakernel(Args args) {
;     ...
;         if (even) {
;             GSYNC();
.LBB0_906:
	v_readlane_b32 s0, v254, 61
	v_readlane_b32 s1, v254, 62
	s_mov_b64 s[6:7], -1
	s_andn2_b64 vcc, exec, s[0:1]
	s_mov_b64 s[0:1], -1
	s_cbranch_vccnz .LBB0_118
	s_getreg_b32 s4, hwreg(HW_REG_XCC_ID, 0, 4)
	s_waitcnt vmcnt(0)
	s_barrier
	s_and_saveexec_b64 s[0:1], s[68:69]
	s_cbranch_execz .LBB0_959
	v_readlane_b32 s2, v254, 42
	s_waitcnt vmcnt(0) expcnt(0) lgkmcnt(0)
	buffer_inv sc1
	s_and_b32 s10, s4, 15
	s_lshl_b32 s5, s10, 8
	v_mov_b32_e32 v0, s2
	ds_read_b32 v2, v0
	v_readlane_b32 s2, v254, 43
	s_add_u32 s12, s46, s5
	s_addc_u32 s13, s47, 0
	v_mov_b32_e32 v3, 1
	v_mov_b32_e32 v0, s2
	ds_read_b32 v6, v0
	v_mov_b32_e32 v5, 0x1400
	s_waitcnt lgkmcnt(0)
	global_atomic_add v3, v5, v3, s[12:13] sc0
	v_cvt_f32_u32_e32 v4, v2
	s_waitcnt vmcnt(0)
	v_mov_b32_e32 v5, v3
	v_sub_u32_e32 v3, 0, v2
	v_rcp_iflag_f32_e32 v4, v4
	s_nop 0
	v_mul_f32_e32 v4, 0x4f7ffffe, v4
	v_cvt_u32_f32_e32 v4, v4
	v_mul_lo_u32 v1, v3, v4
	v_mul_hi_u32 v1, v4, v1
	v_add_u32_e32 v1, v4, v1
	v_mul_hi_u32 v1, v5, v1
	v_mul_lo_u32 v3, v1, v2
	v_sub_u32_e32 v3, v5, v3
	v_add_u32_e32 v4, 1, v1
	v_cmp_ge_u32_e32 vcc, v3, v2
	s_nop 1
	v_cndmask_b32_e32 v1, v1, v4, vcc
	v_sub_u32_e32 v4, v3, v2
	v_cndmask_b32_e32 v3, v3, v4, vcc
	v_add_u32_e32 v4, 1, v1
	v_cmp_ge_u32_e32 vcc, v3, v2
	v_add_u32_e32 v3, 1, v5
	s_nop 0
	v_cndmask_b32_e32 v1, v1, v4, vcc
	v_mul_lo_u32 v4, v2, v1
	v_add_u32_e32 v2, v4, v2
	v_mul_lo_u32 v7, v1, v6
	v_cmp_ne_u32_e32 vcc, v3, v2
	s_mov_b32 s8, 0
	s_cbranch_vccnz .Lnb_loop_11
	buffer_wbl2 sc1
	s_waitcnt vmcnt(0)
	s_mov_b64 exec, 0xffff
	v_mbcnt_lo_u32_b32 v9, -1, 0
	v_mov_b32_e32 v8, 1
	v_lshlrev_b32_e32 v9, 8, v9
	v_add_u32_e32 v9, 0x2404, v9
	global_atomic_add v9, v8, s[46:47]
	s_mov_b64 exec, 1
